# speedup vs baseline: 1.0540x; 1.0054x over previous
; DEV unsigned xb_ld(unsigned* p) { return __hip_atomic_load(p, __ATOMIC_RELAXED, __HIP_MEMORY_SCOPE_AGENT); }
; DEV unsigned xb_add(unsigned* p, unsigned v) { return __hip_atomic_fetch_add(p, v, __ATOMIC_RELAXED, __HIP_MEMORY_SCOPE_AGENT); }
; #define XB_SPIN(cond, bar) do { unsigned _sp = 0; while (cond) { __builtin_amdgcn_s_sleep(1); \
;     if ((++_sp & 255u) == 0u) { if (xb_ld(&(bar)[XB_TMO])) break; if (_sp > XB_SPIN_CAP) { atomicAdd(&(bar)[XB_TMO], 1u); break; } } } } while (0)
; #define GSYNC() xcd_barrier(p.xbar, s_xb)
; DEV void xcd_barrier(unsigned* bar, volatile unsigned* st) {
;   asm volatile("s_waitcnt vmcnt(0)" ::: "memory");
;   __syncthreads();
;   if (threadIdx.x == 0) {
;     XcdBarrier b; b.bar = bar; b.x = st[0]; b.nloc = st[1]; b.nx = st[2];
;     __builtin_amdgcn_s_waitcnt(0);
;     const unsigned old = xb_add(&bar[XB_XSUB(b.x)], 1u);
;     const unsigned gen = old / b.nloc;
;     if (old + 1u == (gen + 1u) * b.nloc) {
;       __builtin_amdgcn_fence(__ATOMIC_RELEASE, "agent");
;       asm volatile("s_waitcnt vmcnt(0)" ::: "memory");
;       const unsigned og = xb_add(&bar[XB_TOP], 1u);
;       const unsigned tg = og / b.nx;
;       if (og + 1u == (tg + 1u) * b.nx) xb_add(&bar[XB_TOPGEN], 1u);
;       else XB_SPIN(xb_ld(&bar[XB_TOPGEN]) == tg, bar);
;       __builtin_amdgcn_fence(__ATOMIC_ACQUIRE, "agent");
;       xb_add(&bar[XB_XGEN(b.x)], 1u);
;     } else {
;       XB_SPIN(xb_ld(&bar[XB_XGEN(b.x)]) == gen, bar);
;       __builtin_amdgcn_fence(__ATOMIC_ACQUIRE, "agent");
;     }
;   }
;   __syncthreads();
; }
; __global__ void __launch_bounds__(NTHREADS, 2) fwd_megakernel(Params p) {
;     ...
;   phase_prep(p);
;   GSYNC();
.LBB0_86:
	s_or_b64 exec, exec, s[4:5]
	s_waitcnt vmcnt(0)
	s_waitcnt lgkmcnt(0)
	s_barrier
	s_mov_b64 s[0:1], exec
	v_readlane_b32 s2, v254, 40
	v_readlane_b32 s3, v254, 41
	s_and_b64 s[2:3], s[0:1], s[2:3]
	s_mov_b64 exec, s[2:3]
	s_branch .LBB0_119
	s_mov_b64 s[2:3], src_shared_base
	v_mov_b32_e32 v0, 0x12200
	v_mov_b32_e32 v1, s3
	flat_load_dword v2, v[0:1] sc0 sc1
	s_waitcnt vmcnt(0)
	v_mov_b32_e32 v0, 0x12204
	flat_load_dword v6, v[0:1] sc0 sc1
	s_waitcnt vmcnt(0)
	v_mov_b32_e32 v0, 0x12208
	v_mov_b32_e32 v3, 0
	flat_load_dword v0, v[0:1] sc0 sc1
	s_waitcnt vmcnt(0)
	v_mov_b32_e32 v1, 1
	s_waitcnt vmcnt(0) expcnt(0) lgkmcnt(0)
	v_lshlrev_b32_e32 v4, 6, v2
	v_add_u32_e32 v2, 0x500, v4
	v_lshl_add_u64 v[8:9], v[2:3], 2, s[28:29]
	global_atomic_add v1, v[8:9], v1, off sc0
	v_cvt_f32_u32_e32 v2, v6
	v_sub_u32_e32 v5, 0, v6
	v_rcp_iflag_f32_e32 v2, v2
	s_nop 0
	v_mul_f32_e32 v2, 0x4f7ffffe, v2
	v_cvt_u32_f32_e32 v2, v2
	v_mul_lo_u32 v5, v5, v2
	v_mul_hi_u32 v5, v2, v5
	v_add_u32_e32 v2, v2, v5
	s_waitcnt vmcnt(0)
	v_mul_hi_u32 v2, v1, v2
	v_mul_lo_u32 v5, v2, v6
	v_sub_u32_e32 v5, v1, v5
	v_cmp_ge_u32_e32 vcc, v5, v6
	v_add_u32_e32 v7, 1, v2
	v_add_u32_e32 v1, 1, v1
	v_cndmask_b32_e32 v2, v2, v7, vcc
	v_sub_u32_e32 v7, v5, v6
	v_cndmask_b32_e32 v5, v5, v7, vcc
	v_cmp_ge_u32_e32 vcc, v5, v6
	v_add_u32_e32 v5, 1, v2
	s_nop 0
	v_cndmask_b32_e32 v5, v2, v5, vcc
	v_mad_u64_u32 v[6:7], s[2:3], v6, v5, v[6:7]
	v_cmp_ne_u32_e32 vcc, v1, v6
	s_and_saveexec_b64 s[2:3], vcc
	s_xor_b64 s[2:3], exec, s[2:3]
	s_cbranch_execz .LBB0_101
	v_add_u32_e32 v2, 0x900, v4
	v_lshl_add_u64 v[0:1], v[2:3], 2, s[28:29]
	global_load_dword v2, v[0:1], off sc1
	s_waitcnt vmcnt(0)
	v_cmp_eq_u32_e32 vcc, v2, v5
	s_and_saveexec_b64 s[4:5], vcc
	s_cbranch_execz .LBB0_100
	s_mov_b32 s16, 1
	s_mov_b64 s[6:7], 0
	v_mov_b32_e32 v2, 0
	s_branch .LBB0_91

; DEV void phase_filt_mlp(const Params& p, int layer, char* smem) {
;     ...
;     for (int idx = tid; idx < 512; idx += NTHREADS) {
;       int pp = idx >> 6, j = idx & 63;
;       float a = b1[j];
;       for (int f = 0; f < 33; ++f) a += feats[pp * 33 + f] * w1[f * 64 + j];
;       h1[pp * 64 + j] = sinf(fq[j] * a);
;     }
.LBB0_134:
	v_lshl_add_u64 v[12:13], v[4:5], 0, s[2:3]
	global_load_dword v24, v[12:13], off
	global_load_dword v25, v[12:13], off offset:256
	global_load_dword v26, v[12:13], off offset:512
	global_load_dword v27, v[12:13], off offset:768
	global_load_dword v28, v[12:13], off offset:1024
	global_load_dword v29, v[12:13], off offset:1280
	global_load_dword v30, v[12:13], off offset:1536
	global_load_dword v31, v[12:13], off offset:1792
	global_load_dword v43, v[12:13], off offset:2048
	global_load_dword v44, v[12:13], off offset:2304
	global_load_dword v45, v[12:13], off offset:2560
	ds_read2_b32 v[32:33], v7 offset0:0 offset1:1
	ds_read2_b32 v[34:35], v7 offset0:2 offset1:3
	ds_read2_b32 v[36:37], v7 offset0:4 offset1:5
	ds_read2_b32 v[38:39], v7 offset0:6 offset1:7
	ds_read2_b32 v[40:41], v7 offset0:8 offset1:9
	ds_read_b32 v42, v7 offset:40
	s_add_u32 s2, s2, 0xb00
	s_addc_u32 s3, s3, 0
	s_cmpk_eq_i32 s2, 0x2100
	v_add_u32_e32 v7, 44, v7
	s_waitcnt vmcnt(0) lgkmcnt(0)
	v_fmac_f32_e32 v8, v32, v24
	v_fmac_f32_e32 v8, v33, v25
	v_fmac_f32_e32 v8, v34, v26
	v_fmac_f32_e32 v8, v35, v27
	v_fmac_f32_e32 v8, v36, v28
	v_fmac_f32_e32 v8, v37, v29
	v_fmac_f32_e32 v8, v38, v30
	v_fmac_f32_e32 v8, v39, v31
	v_fmac_f32_e32 v8, v40, v43
	v_fmac_f32_e32 v8, v41, v44
	v_fmac_f32_e32 v8, v42, v45
	s_cbranch_scc0 .LBB0_134
	v_mul_f32_e32 v7, v8, v6
	v_and_b32_e32 v8, 0x7fffffff, v7
	v_cmp_nlt_f32_e64 s[2:3], |v7|, s95
	s_and_saveexec_b64 s[4:5], s[2:3]
	s_xor_b64 s[22:23], exec, s[4:5]
	s_cbranch_execz .LBB0_137
	v_lshrrev_b32_e32 v9, 23, v8
	v_add_u32_e32 v9, 0xffffff88, v9
	v_cmp_lt_u32_e64 s[2:3], 63, v9
	s_mov_b32 s8, 0xfe5163ab
	s_nop 0
	v_cndmask_b32_e64 v10, 0, v181, s[2:3]
	v_add_u32_e32 v9, v10, v9
	v_cmp_lt_u32_e64 s[4:5], 31, v9
	s_nop 1
	v_cndmask_b32_e64 v10, 0, v182, s[4:5]
	v_add_u32_e32 v9, v10, v9
	v_cmp_lt_u32_e64 s[6:7], 31, v9
	s_nop 1
	v_cndmask_b32_e64 v10, 0, v182, s[6:7]
	v_add_u32_e32 v9, v10, v9
	v_and_b32_e32 v10, 0x7fffff, v8
	v_or_b32_e32 v22, 0x800000, v10
	v_mad_u64_u32 v[10:11], s[8:9], v22, s8, 0
	v_mov_b32_e32 v128, v11
	s_mov_b32 s8, 0x3c439041
	v_mad_u64_u32 v[12:13], s[8:9], v22, s8, v[128:129]
	v_mov_b32_e32 v128, v13
	s_mov_b32 s8, 0xdb629599
	v_mad_u64_u32 v[14:15], s[8:9], v22, s8, v[128:129]
	v_mov_b32_e32 v128, v15
	s_mov_b32 s8, 0xf534ddc0
	v_mad_u64_u32 v[16:17], s[8:9], v22, s8, v[128:129]
	v_mov_b32_e32 v128, v17
	s_mov_b32 s8, 0xfc2757d1
	v_mad_u64_u32 v[18:19], s[8:9], v22, s8, v[128:129]
	v_mov_b32_e32 v128, v19
	s_mov_b32 s8, 0x4e441529
	v_mad_u64_u32 v[20:21], s[8:9], v22, s8, v[128:129]
	v_mov_b32_e32 v128, v21
	s_mov_b32 s8, 0xa2f9836e
	v_mad_u64_u32 v[22:23], s[8:9], v22, s8, v[128:129]
	v_cndmask_b32_e64 v11, v20, v16, s[2:3]
	v_cndmask_b32_e64 v13, v22, v18, s[2:3]
	v_cndmask_b32_e64 v17, v23, v20, s[2:3]
	v_cndmask_b32_e64 v15, v13, v11, s[4:5]
	v_cndmask_b32_e64 v13, v17, v13, s[4:5]
	v_cndmask_b32_e64 v17, v18, v14, s[2:3]
	v_cndmask_b32_e64 v11, v11, v17, s[4:5]
	v_cndmask_b32_e64 v13, v13, v15, s[6:7]
	v_cndmask_b32_e64 v15, v15, v11, s[6:7]
	v_sub_u32_e32 v18, 32, v9
	v_alignbit_b32 v19, v13, v15, v18
	v_cmp_eq_u32_e64 s[8:9], 0, v9
	v_cndmask_b32_e64 v12, v16, v12, s[2:3]
	v_cndmask_b32_e64 v10, v14, v10, s[2:3]
	v_cndmask_b32_e64 v9, v19, v13, s[8:9]
	v_cndmask_b32_e64 v13, v17, v12, s[4:5]
	v_cndmask_b32_e64 v11, v11, v13, s[6:7]
	v_alignbit_b32 v16, v15, v11, v18
	v_cndmask_b32_e64 v15, v16, v15, s[8:9]
	v_bfe_u32 v19, v9, 29, 1
	v_cndmask_b32_e64 v10, v12, v10, s[4:5]
	v_alignbit_b32 v16, v9, v15, 30
	v_sub_u32_e32 v20, 0, v19
	v_cndmask_b32_e64 v10, v13, v10, s[6:7]
	v_xor_b32_e32 v16, v16, v20
	v_alignbit_b32 v12, v11, v10, v18
	v_cndmask_b32_e64 v11, v12, v11, s[8:9]
	v_ffbh_u32_e32 v13, v16
	v_alignbit_b32 v12, v15, v11, 30
	v_min_u32_e32 v13, 32, v13
	v_alignbit_b32 v10, v11, v10, 30
	v_xor_b32_e32 v12, v12, v20
	v_sub_u32_e32 v14, 31, v13
	v_xor_b32_e32 v10, v10, v20
	v_alignbit_b32 v15, v16, v12, v14
	v_alignbit_b32 v10, v12, v10, v14
	v_alignbit_b32 v11, v15, v10, 9
	v_ffbh_u32_e32 v12, v11
	v_min_u32_e32 v12, 32, v12
	v_lshrrev_b32_e32 v17, 29, v9
	v_not_b32_e32 v14, v12
	v_alignbit_b32 v10, v11, v10, v14
	v_lshlrev_b32_e32 v11, 31, v17
	v_or_b32_e32 v14, 0x33000000, v11
	v_add_lshl_u32 v12, v12, v13, 23
	v_lshrrev_b32_e32 v10, 9, v10
	v_sub_u32_e32 v12, v14, v12
	v_or_b32_e32 v11, 0.5, v11
	v_lshlrev_b32_e32 v13, 23, v13
	v_or_b32_e32 v10, v12, v10
	v_lshrrev_b32_e32 v12, 9, v15
	v_sub_u32_e32 v11, v11, v13
	v_or_b32_e32 v11, v12, v11
	v_mul_f32_e32 v12, 0x3fc90fda, v11
	s_mov_b32 s2, 0x3fc90fda
	v_fma_f32 v13, v11, s2, -v12
	v_fmac_f32_e32 v13, 0x33a22168, v11
	v_fmac_f32_e32 v13, 0x3fc90fda, v10
	v_lshrrev_b32_e32 v9, 30, v9
	v_add_f32_e32 v10, v12, v13
	v_add_u32_e32 v9, v19, v9

; DEV void hyena_item(const Params& p, int layer, int item, char* smem) {
;     ...
;   fft_fwd(buf, tid);
; #pragma unroll 8
;   for (int j = 0; j < 32; ++j) {
;     int i = tid + 256 * j;
;     buf[fphys(i)] = cmul(buf[fphys(i)], K0[i]);
;   }
.LBB0_433:
	s_or_b64 exec, exec, s[34:35]
	v_readlane_b32 s36, v254, 8
	s_lshl_b32 vcc_lo, s84, 16
	s_mov_b32 vcc_hi, s94
	v_readlane_b32 s50, v254, 22
	v_ashrrev_i32_e32 v9, 31, v8
	v_readlane_b32 s4, v254, 57
	v_readlane_b32 s51, v254, 23
	s_add_u32 s0, s50, vcc_lo
	v_lshl_add_u64 v[24:25], v[8:9], 3, vcc
	v_readlane_b32 s5, v254, 58
	s_addc_u32 s1, s51, 0
	v_mov_b32_e32 v9, v61
	v_lshl_add_u64 v[26:27], s[4:5], 0, v[24:25]
	s_mov_b32 s4, 0
	s_mov_b64 s[6:7], 0x4000
	v_readlane_b32 s37, v254, 9
	v_readlane_b32 s38, v254, 10
	v_readlane_b32 s39, v254, 11
	v_readlane_b32 s40, v254, 12
	v_readlane_b32 s41, v254, 13
	v_readlane_b32 s42, v254, 14
	v_readlane_b32 s43, v254, 15
	v_readlane_b32 s44, v254, 16
	v_readlane_b32 s45, v254, 17
	v_readlane_b32 s46, v254, 18
	v_readlane_b32 s47, v254, 19
	v_readlane_b32 s48, v254, 20
	v_readlane_b32 s49, v254, 21
	s_waitcnt lgkmcnt(0)
	s_barrier
	v_add_u32_e32 v17, s4, v8
	global_load_dwordx2 v[36:37], v[26:27], off offset:-2048
	global_load_dwordx2 v[38:39], v[26:27], off
	v_add_u32_e32 v28, 0x200, v17
	v_ashrrev_i32_e32 v29, 31, v28
	v_lshl_add_u64 v[28:29], v[28:29], 3, s[0:1]
	global_load_dwordx2 v[40:41], v[28:29], off
	v_add_u32_e32 v28, 0x300, v17
	v_ashrrev_i32_e32 v29, 31, v28
	v_lshl_add_u64 v[28:29], v[28:29], 3, s[0:1]
	global_load_dwordx2 v[42:43], v[28:29], off
	v_add_u32_e32 v28, 0x400, v17
	v_ashrrev_i32_e32 v29, 31, v28
	v_lshl_add_u64 v[28:29], v[28:29], 3, s[0:1]
	global_load_dwordx2 v[44:45], v[28:29], off
	v_add_u32_e32 v28, 0x500, v17
	v_ashrrev_i32_e32 v29, 31, v28
	v_lshl_add_u64 v[28:29], v[28:29], 3, s[0:1]
	global_load_dwordx2 v[46:47], v[28:29], off
	v_add_u32_e32 v28, 0x600, v17
	v_ashrrev_i32_e32 v29, 31, v28
	v_lshl_add_u64 v[28:29], v[28:29], 3, s[0:1]
	global_load_dwordx2 v[48:49], v[28:29], off
	v_add_u32_e32 v28, 0x700, v17
	v_ashrrev_i32_e32 v29, 31, v28
	v_lshl_add_u64 v[28:29], v[28:29], 3, s[0:1]
	global_load_dwordx2 v[50:51], v[28:29], off
.LBB0_434:
	v_add_u32_e32 v17, s4, v8
	v_lshl_add_u64 v[26:27], v[26:27], 0, s[6:7]
	s_addk_i32 s4, 0x800
	s_cmpk_eq_i32 s4, 0x2000
	v_and_b32_e32 v19, -8, v17
	v_add_u32_e32 v19, v9, v19
	ds_read_b64 v[30:31], v19
	s_waitcnt vmcnt(0)
	v_add_u32_e32 v54, 0x100, v17
	v_and_b32_e32 v54, -8, v54
	v_add_u32_e32 v54, v9, v54
	ds_read_b64 v[52:53], v54 offset:2048
	s_waitcnt lgkmcnt(1)
	v_pk_mul_f32 v[32:33], v[30:31], v[36:37] op_sel:[1,1] op_sel_hi:[0,1]
	v_pk_fma_f32 v[34:35], v[30:31], v[36:37], v[32:33] neg_lo:[0,0,1] neg_hi:[0,0,1]
	v_pk_fma_f32 v[28:29], v[30:31], v[36:37], v[32:33] op_sel_hi:[1,0,1]
	s_nop 0
	v_mov_b32_e32 v35, v29
	ds_write_b64 v19, v[34:35]
	s_cbranch_scc1 .Lkh_a_0
	global_load_dwordx2 v[36:37], v[26:27], off offset:-2048
.Lkh_a_0:
	v_add_u32_e32 v19, 0x200, v17
	v_and_b32_e32 v19, -8, v19
	v_add_u32_e32 v19, v9, v19
	ds_read_b64 v[30:31], v19 offset:4096
	s_waitcnt lgkmcnt(2)
	v_pk_mul_f32 v[32:33], v[52:53], v[38:39] op_sel:[1,1] op_sel_hi:[0,1]
	v_pk_fma_f32 v[56:57], v[52:53], v[38:39], v[32:33] neg_lo:[0,0,1] neg_hi:[0,0,1]
	v_pk_fma_f32 v[28:29], v[52:53], v[38:39], v[32:33] op_sel_hi:[1,0,1]
	s_nop 0
	v_mov_b32_e32 v57, v29
	ds_write_b64 v54, v[56:57] offset:2048
	s_cbranch_scc1 .Lkh_a_1
	global_load_dwordx2 v[38:39], v[26:27], off
.Lkh_a_1:
	v_add_u32_e32 v54, 0x300, v17
	v_and_b32_e32 v54, -8, v54
	v_add_u32_e32 v54, v9, v54
	ds_read_b64 v[52:53], v54 offset:6144
	s_waitcnt lgkmcnt(2)
	v_pk_mul_f32 v[32:33], v[30:31], v[40:41] op_sel:[1,1] op_sel_hi:[0,1]
	v_pk_fma_f32 v[34:35], v[30:31], v[40:41], v[32:33] neg_lo:[0,0,1] neg_hi:[0,0,1]
	v_pk_fma_f32 v[28:29], v[30:31], v[40:41], v[32:33] op_sel_hi:[1,0,1]
	s_nop 0
	v_mov_b32_e32 v35, v29
	ds_write_b64 v19, v[34:35] offset:4096
	s_cbranch_scc1 .Lkh_a_2
	v_add_u32_e32 v28, 0xa00, v17
	v_ashrrev_i32_e32 v29, 31, v28
	v_lshl_add_u64 v[28:29], v[28:29], 3, s[0:1]
	global_load_dwordx2 v[40:41], v[28:29], off
.Lkh_a_2:
	v_add_u32_e32 v19, 0x400, v17
	v_and_b32_e32 v19, -8, v19
	v_add_u32_e32 v19, v9, v19
	ds_read_b64 v[30:31], v19 offset:8192
	s_waitcnt lgkmcnt(2)
	v_pk_mul_f32 v[32:33], v[52:53], v[42:43] op_sel:[1,1] op_sel_hi:[0,1]
	v_pk_fma_f32 v[56:57], v[52:53], v[42:43], v[32:33] neg_lo:[0,0,1] neg_hi:[0,0,1]
	v_pk_fma_f32 v[28:29], v[52:53], v[42:43], v[32:33] op_sel_hi:[1,0,1]
	s_nop 0
	v_mov_b32_e32 v57, v29
	ds_write_b64 v54, v[56:57] offset:6144
	s_cbranch_scc1 .Lkh_a_3
	v_add_u32_e32 v28, 0xb00, v17
	v_ashrrev_i32_e32 v29, 31, v28
	v_lshl_add_u64 v[28:29], v[28:29], 3, s[0:1]
	global_load_dwordx2 v[42:43], v[28:29], off
.Lkh_a_3:
	v_add_u32_e32 v54, 0x500, v17
	v_and_b32_e32 v54, -8, v54
	v_add_u32_e32 v54, v9, v54
	ds_read_b64 v[52:53], v54 offset:10240
	s_waitcnt lgkmcnt(2)
	v_pk_mul_f32 v[32:33], v[30:31], v[44:45] op_sel:[1,1] op_sel_hi:[0,1]
	v_pk_fma_f32 v[34:35], v[30:31], v[44:45], v[32:33] neg_lo:[0,0,1] neg_hi:[0,0,1]
	v_pk_fma_f32 v[28:29], v[30:31], v[44:45], v[32:33] op_sel_hi:[1,0,1]
	s_nop 0
	v_mov_b32_e32 v35, v29
	ds_write_b64 v19, v[34:35] offset:8192
	s_cbranch_scc1 .Lkh_a_4
	v_add_u32_e32 v28, 0xc00, v17
	v_ashrrev_i32_e32 v29, 31, v28
	v_lshl_add_u64 v[28:29], v[28:29], 3, s[0:1]
	global_load_dwordx2 v[44:45], v[28:29], off
; DEV void hyena_item(const Params& p, int layer, int item, char* smem) {
;     ...
; #pragma unroll 8
;   for (int j = 0; j < 32; ++j) {
;     int i = tid + 256 * j;
;     buf[fphys(i)] = cmul(buf[fphys(i)], K0[i]);
;   }
;   __syncthreads();
;   fft_inv(buf, tid);
.Lkh_a_4:
	v_add_u32_e32 v19, 0x600, v17
	v_and_b32_e32 v19, -8, v19
	v_add_u32_e32 v19, v9, v19
	ds_read_b64 v[30:31], v19 offset:12288
	s_waitcnt lgkmcnt(2)
	v_pk_mul_f32 v[32:33], v[52:53], v[46:47] op_sel:[1,1] op_sel_hi:[0,1]
	v_pk_fma_f32 v[56:57], v[52:53], v[46:47], v[32:33] neg_lo:[0,0,1] neg_hi:[0,0,1]
	v_pk_fma_f32 v[28:29], v[52:53], v[46:47], v[32:33] op_sel_hi:[1,0,1]
	s_nop 0
	v_mov_b32_e32 v57, v29
	ds_write_b64 v54, v[56:57] offset:10240
	s_cbranch_scc1 .Lkh_a_5
	v_add_u32_e32 v28, 0xd00, v17
	v_ashrrev_i32_e32 v29, 31, v28
	v_lshl_add_u64 v[28:29], v[28:29], 3, s[0:1]
	global_load_dwordx2 v[46:47], v[28:29], off
.Lkh_a_5:
	v_add_u32_e32 v54, 0x700, v17
	v_and_b32_e32 v54, -8, v54
	v_add_u32_e32 v54, v9, v54
	ds_read_b64 v[52:53], v54 offset:14336
	s_waitcnt lgkmcnt(2)
	v_pk_mul_f32 v[32:33], v[30:31], v[48:49] op_sel:[1,1] op_sel_hi:[0,1]
	v_pk_fma_f32 v[34:35], v[30:31], v[48:49], v[32:33] neg_lo:[0,0,1] neg_hi:[0,0,1]
	v_pk_fma_f32 v[28:29], v[30:31], v[48:49], v[32:33] op_sel_hi:[1,0,1]
	s_nop 0
	v_mov_b32_e32 v35, v29
	ds_write_b64 v19, v[34:35] offset:12288
	s_cbranch_scc1 .Lkh_a_6
	v_add_u32_e32 v28, 0xe00, v17
	v_ashrrev_i32_e32 v29, 31, v28
	v_lshl_add_u64 v[28:29], v[28:29], 3, s[0:1]
	global_load_dwordx2 v[48:49], v[28:29], off
.Lkh_a_6:
	s_waitcnt lgkmcnt(1)
	v_pk_mul_f32 v[32:33], v[52:53], v[50:51] op_sel:[1,1] op_sel_hi:[0,1]
	v_pk_fma_f32 v[56:57], v[52:53], v[50:51], v[32:33] neg_lo:[0,0,1] neg_hi:[0,0,1]
	v_pk_fma_f32 v[28:29], v[52:53], v[50:51], v[32:33] op_sel_hi:[1,0,1]
	s_nop 0
	v_mov_b32_e32 v57, v29
	ds_write_b64 v54, v[56:57] offset:14336
	s_cbranch_scc1 .Lkh_a_7
	v_add_u32_e32 v28, 0xf00, v17
	v_ashrrev_i32_e32 v29, 31, v28
	v_lshl_add_u64 v[28:29], v[28:29], 3, s[0:1]
	global_load_dwordx2 v[50:51], v[28:29], off
.Lkh_a_7:
	v_add_u32_e32 v9, 0x4000, v9
	s_cbranch_scc0 .LBB0_434
	s_waitcnt lgkmcnt(0)
	s_barrier
	s_and_saveexec_b64 s[60:61], s[2:3]
	s_cbranch_execz .LBB0_445
	v_add_u32_e32 v9, 0xff, v65
	s_movk_i32 s0, 0x2100
	s_movk_i32 s4, 0x20ff
	v_cmp_gt_u32_e64 s[0:1], s0, v9
	v_cmp_lt_u32_e64 s[4:5], s4, v9
	v_mov_b32_e32 v21, v8
	s_and_saveexec_b64 s[20:21], s[4:5]
	s_cbranch_execz .LBB0_442
	v_lshrrev_b32_e32 v9, 8, v9
	s_movk_i32 s4, 0x48
	v_mul_lo_u32 v17, v8, s4
	v_mul_hi_u32_u24_e32 v19, 0x4800, v9
	s_movk_i32 s6, 0x4800
	v_cmp_ne_u32_e64 s[4:5], 0, v19
	v_mad_u32_u24 v19, v9, s6, v17
	v_cmp_lt_u32_e64 s[6:7], v19, v17
	v_add_u32_e32 v21, 8, v17
	v_add_u32_e32 v23, 8, v19
	s_or_b64 s[22:23], s[6:7], s[4:5]
	v_cmp_lt_u32_e64 s[6:7], v23, v21
	v_add_u32_e32 v21, 12, v17
	v_add_u32_e32 v23, 12, v19
	s_or_b64 s[24:25], s[6:7], s[4:5]
	v_cmp_lt_u32_e64 s[6:7], v23, v21
	v_add_u32_e32 v21, 16, v17
	v_add_u32_e32 v23, 16, v19
	s_or_b64 s[28:29], s[6:7], s[4:5]
	v_cmp_lt_u32_e64 s[6:7], v23, v21
	v_add_u32_e32 v21, 20, v17
	v_add_u32_e32 v23, 20, v19
	s_or_b64 s[30:31], s[6:7], s[4:5]
	v_cmp_lt_u32_e64 s[6:7], v23, v21
	v_add_u32_e32 v21, 24, v17
	v_add_u32_e32 v23, 24, v19
	s_or_b64 s[36:37], s[6:7], s[4:5]
	v_cmp_lt_u32_e64 s[6:7], v23, v21
	v_add_u32_e32 v21, 28, v17
	v_add_u32_e32 v23, 28, v19
	s_or_b64 s[38:39], s[6:7], s[4:5]
	v_cmp_lt_u32_e64 s[6:7], v23, v21
	v_add_u32_e32 v21, 32, v17
	v_add_u32_e32 v23, 32, v19
	s_or_b64 s[40:41], s[6:7], s[4:5]
	v_cmp_lt_u32_e64 s[6:7], v23, v21
	v_add_u32_e32 v21, 36, v17
	v_add_u32_e32 v23, 36, v19
	s_or_b64 s[42:43], s[6:7], s[4:5]
	v_cmp_lt_u32_e64 s[6:7], v23, v21
	v_add_u32_e32 v21, 40, v17
	v_add_u32_e32 v23, 40, v19
	s_or_b64 s[44:45], s[6:7], s[4:5]
	v_cmp_lt_u32_e64 s[6:7], v23, v21
	v_add_u32_e32 v21, 44, v17
	v_add_u32_e32 v23, 44, v19
	s_or_b64 s[46:47], s[6:7], s[4:5]
	v_cmp_lt_u32_e64 s[6:7], v23, v21
	v_add_u32_e32 v21, 48, v17
	v_add_u32_e32 v23, 48, v19
	s_or_b64 s[48:49], s[6:7], s[4:5]
	v_cmp_lt_u32_e64 s[6:7], v23, v21
	v_add_u32_e32 v21, 52, v17
	v_add_u32_e32 v23, 52, v19
	s_or_b64 s[50:51], s[6:7], s[4:5]
	v_cmp_lt_u32_e64 s[6:7], v23, v21
	v_add_u32_e32 v21, 56, v17
	v_add_u32_e32 v23, 56, v19
	s_or_b64 s[92:93], s[6:7], s[4:5]
	v_cmp_lt_u32_e64 s[6:7], v23, v21
	v_add_u32_e32 v17, 60, v17
	v_add_u32_e32 v19, 60, v19
	s_or_b64 s[96:97], s[6:7], s[4:5]
	v_cmp_lt_u32_e64 s[6:7], v19, v17
	s_or_b64 s[4:5], s[6:7], s[4:5]
	s_or_b64 s[6:7], s[22:23], s[24:25]
	s_or_b64 s[6:7], s[6:7], s[28:29]
	s_or_b64 s[6:7], s[6:7], s[30:31]
	s_or_b64 s[6:7], s[6:7], s[36:37]
	s_or_b64 s[6:7], s[6:7], s[38:39]
	s_or_b64 s[6:7], s[6:7], s[40:41]
	s_or_b64 s[6:7], s[6:7], s[42:43]
	s_or_b64 s[6:7], s[6:7], s[44:45]
	s_or_b64 s[6:7], s[6:7], s[46:47]
	s_or_b64 s[6:7], s[6:7], s[48:49]
	s_or_b64 s[6:7], s[6:7], s[50:51]
	s_or_b64 s[6:7], s[6:7], s[92:93]
	s_or_b64 s[6:7], s[6:7], s[96:97]
	s_nor_b64 s[22:23], s[6:7], s[4:5]
	s_mov_b64 s[4:5], -1
	v_mov_b32_e32 v21, v8
	s_and_saveexec_b64 s[6:7], s[22:23]
	s_cbranch_execz .LBB0_441
	v_add_u32_e32 v17, 1, v9
	v_and_b32_e32 v19, 0x1fffffe, v17
	v_add_u32_e32 v9, 0x100, v8
	s_mov_b64 s[22:23], 0
	v_mov_b32_e32 v21, v19
	v_mov_b64_e32 v[26:27], v[8:9]

; DEV void hyena_item(const Params& p, int layer, int item, char* smem) {
;     ...
;   fft_fwd(buf, tid);
; #pragma unroll 8
;   for (int j = 0; j < 32; ++j) {
;     int i = tid + 256 * j;
;     buf[fphys(i)] = cmul(buf[fphys(i)], K1[i]);
;   }
.LBB0_475:
	s_or_b64 exec, exec, s[60:61]
	v_readlane_b32 s36, v254, 8
	s_or_b32 s0, vcc_lo, 0x1000000
	v_readlane_b32 s50, v254, 22
	v_readlane_b32 s4, v254, 59
	v_readlane_b32 s51, v254, 23
	s_add_u32 s0, s50, s0
	v_readlane_b32 s5, v254, 60
	s_addc_u32 s1, s51, 0
	v_mov_b32_e32 v9, v61
	v_lshl_add_u64 v[10:11], s[4:5], 0, v[24:25]
	s_mov_b32 s4, 0
	s_mov_b64 s[6:7], 0x4000
	v_readlane_b32 s37, v254, 9
	v_readlane_b32 s38, v254, 10
	v_readlane_b32 s39, v254, 11
	v_readlane_b32 s40, v254, 12
	v_readlane_b32 s41, v254, 13
	v_readlane_b32 s42, v254, 14
	v_readlane_b32 s43, v254, 15
	v_readlane_b32 s44, v254, 16
	v_readlane_b32 s45, v254, 17
	v_readlane_b32 s46, v254, 18
	v_readlane_b32 s47, v254, 19
	v_readlane_b32 s48, v254, 20
	v_readlane_b32 s49, v254, 21
	s_waitcnt lgkmcnt(0)
	s_barrier
	v_add_u32_e32 v20, s4, v8
	global_load_dwordx2 v[36:37], v[10:11], off offset:-2052
	global_load_dwordx2 v[38:39], v[10:11], off offset:-4
	v_add_u32_e32 v12, 0x200, v20
	v_ashrrev_i32_e32 v13, 31, v12
	v_lshl_add_u64 v[12:13], v[12:13], 3, s[0:1]
	global_load_dwordx2 v[40:41], v[12:13], off
	v_add_u32_e32 v12, 0x300, v20
	v_ashrrev_i32_e32 v13, 31, v12
	v_lshl_add_u64 v[12:13], v[12:13], 3, s[0:1]
	global_load_dwordx2 v[42:43], v[12:13], off
	v_add_u32_e32 v12, 0x400, v20
	v_ashrrev_i32_e32 v13, 31, v12
	v_lshl_add_u64 v[12:13], v[12:13], 3, s[0:1]
	global_load_dwordx2 v[44:45], v[12:13], off
	v_add_u32_e32 v12, 0x500, v20
	v_ashrrev_i32_e32 v13, 31, v12
	v_lshl_add_u64 v[12:13], v[12:13], 3, s[0:1]
	global_load_dwordx2 v[46:47], v[12:13], off
	v_add_u32_e32 v12, 0x600, v20
	v_ashrrev_i32_e32 v13, 31, v12
	v_lshl_add_u64 v[12:13], v[12:13], 3, s[0:1]
	global_load_dwordx2 v[48:49], v[12:13], off
	v_add_u32_e32 v12, 0x700, v20
	v_ashrrev_i32_e32 v13, 31, v12
	v_lshl_add_u64 v[12:13], v[12:13], 3, s[0:1]
	global_load_dwordx2 v[50:51], v[12:13], off
.LBB0_476:
	v_add_u32_e32 v20, s4, v8
	v_lshl_add_u64 v[10:11], v[10:11], 0, s[6:7]
	s_addk_i32 s4, 0x800
	s_cmpk_eq_i32 s4, 0x2000
	v_and_b32_e32 v21, -8, v20
	v_add_u32_e32 v21, v9, v21
	ds_read_b64 v[14:15], v21
	s_waitcnt vmcnt(0)
	v_add_u32_e32 v54, 0x100, v20
	v_and_b32_e32 v54, -8, v54
	v_add_u32_e32 v54, v9, v54
	ds_read_b64 v[52:53], v54 offset:2048
	s_waitcnt lgkmcnt(1)
	v_pk_mul_f32 v[16:17], v[14:15], v[36:37] op_sel:[1,1] op_sel_hi:[0,1]
	v_pk_fma_f32 v[18:19], v[14:15], v[36:37], v[16:17] neg_lo:[0,0,1] neg_hi:[0,0,1]
	v_pk_fma_f32 v[12:13], v[14:15], v[36:37], v[16:17] op_sel_hi:[1,0,1]
	s_nop 0
	v_mov_b32_e32 v19, v13
	ds_write_b64 v21, v[18:19]
	s_cbranch_scc1 .Lkh_b_0
	global_load_dwordx2 v[36:37], v[10:11], off offset:-2052
.Lkh_b_0:
	v_add_u32_e32 v21, 0x200, v20
	v_and_b32_e32 v21, -8, v21
	v_add_u32_e32 v21, v9, v21
	ds_read_b64 v[14:15], v21 offset:4096
	s_waitcnt lgkmcnt(2)
	v_pk_mul_f32 v[16:17], v[52:53], v[38:39] op_sel:[1,1] op_sel_hi:[0,1]
	v_pk_fma_f32 v[56:57], v[52:53], v[38:39], v[16:17] neg_lo:[0,0,1] neg_hi:[0,0,1]
	v_pk_fma_f32 v[12:13], v[52:53], v[38:39], v[16:17] op_sel_hi:[1,0,1]
	s_nop 0
	v_mov_b32_e32 v57, v13
	ds_write_b64 v54, v[56:57] offset:2048
	s_cbranch_scc1 .Lkh_b_1
	global_load_dwordx2 v[38:39], v[10:11], off offset:-4
.Lkh_b_1:
	v_add_u32_e32 v54, 0x300, v20
	v_and_b32_e32 v54, -8, v54
	v_add_u32_e32 v54, v9, v54
	ds_read_b64 v[52:53], v54 offset:6144
	s_waitcnt lgkmcnt(2)
	v_pk_mul_f32 v[16:17], v[14:15], v[40:41] op_sel:[1,1] op_sel_hi:[0,1]
	v_pk_fma_f32 v[18:19], v[14:15], v[40:41], v[16:17] neg_lo:[0,0,1] neg_hi:[0,0,1]
	v_pk_fma_f32 v[12:13], v[14:15], v[40:41], v[16:17] op_sel_hi:[1,0,1]
	s_nop 0
	v_mov_b32_e32 v19, v13
	ds_write_b64 v21, v[18:19] offset:4096
	s_cbranch_scc1 .Lkh_b_2
	v_add_u32_e32 v12, 0xa00, v20
	v_ashrrev_i32_e32 v13, 31, v12
	v_lshl_add_u64 v[12:13], v[12:13], 3, s[0:1]
	global_load_dwordx2 v[40:41], v[12:13], off
.Lkh_b_2:
	v_add_u32_e32 v21, 0x400, v20
	v_and_b32_e32 v21, -8, v21
	v_add_u32_e32 v21, v9, v21
	ds_read_b64 v[14:15], v21 offset:8192
	s_waitcnt lgkmcnt(2)
	v_pk_mul_f32 v[16:17], v[52:53], v[42:43] op_sel:[1,1] op_sel_hi:[0,1]
	v_pk_fma_f32 v[56:57], v[52:53], v[42:43], v[16:17] neg_lo:[0,0,1] neg_hi:[0,0,1]
	v_pk_fma_f32 v[12:13], v[52:53], v[42:43], v[16:17] op_sel_hi:[1,0,1]
	s_nop 0
	v_mov_b32_e32 v57, v13
	ds_write_b64 v54, v[56:57] offset:6144
	s_cbranch_scc1 .Lkh_b_3
	v_add_u32_e32 v12, 0xb00, v20
	v_ashrrev_i32_e32 v13, 31, v12
	v_lshl_add_u64 v[12:13], v[12:13], 3, s[0:1]
	global_load_dwordx2 v[42:43], v[12:13], off
.Lkh_b_3:
	v_add_u32_e32 v54, 0x500, v20
	v_and_b32_e32 v54, -8, v54
	v_add_u32_e32 v54, v9, v54
	ds_read_b64 v[52:53], v54 offset:10240
	s_waitcnt lgkmcnt(2)
	v_pk_mul_f32 v[16:17], v[14:15], v[44:45] op_sel:[1,1] op_sel_hi:[0,1]
	v_pk_fma_f32 v[18:19], v[14:15], v[44:45], v[16:17] neg_lo:[0,0,1] neg_hi:[0,0,1]
	v_pk_fma_f32 v[12:13], v[14:15], v[44:45], v[16:17] op_sel_hi:[1,0,1]
	s_nop 0
	v_mov_b32_e32 v19, v13
	ds_write_b64 v21, v[18:19] offset:8192
	s_cbranch_scc1 .Lkh_b_4
	v_add_u32_e32 v12, 0xc00, v20
	v_ashrrev_i32_e32 v13, 31, v12
	v_lshl_add_u64 v[12:13], v[12:13], 3, s[0:1]
	global_load_dwordx2 v[44:45], v[12:13], off
; template <int R, bool INV>
; DEV void fft_pass(cf* buf, int s_log2, int tid) {
;     ...
;   for (int gi = tid; gi < ngroups; gi += 256) {
;     int hi = gi >> s_log2, lo = gi & (s - 1);
;     int base = (hi << (s_log2 + R)) + lo;
;     cf v[RAD];
; #pragma unroll
;     for (int k = 0; k < RAD; ++k) v[k] = buf[fphys(base + (k << s_log2))];
;     const float frac = (float)lo / (float)(s << R);
; DEV void hyena_item(const Params& p, int layer, int item, char* smem) {
;     ...
; #pragma unroll 8
;   for (int j = 0; j < 32; ++j) {
;     int i = tid + 256 * j;
;     buf[fphys(i)] = cmul(buf[fphys(i)], K0[i]);
;   }
.Lkh_b_4:
	v_add_u32_e32 v21, 0x600, v20
	v_and_b32_e32 v21, -8, v21
	v_add_u32_e32 v21, v9, v21
	ds_read_b64 v[14:15], v21 offset:12288
	s_waitcnt lgkmcnt(2)
	v_pk_mul_f32 v[16:17], v[52:53], v[46:47] op_sel:[1,1] op_sel_hi:[0,1]
	v_pk_fma_f32 v[56:57], v[52:53], v[46:47], v[16:17] neg_lo:[0,0,1] neg_hi:[0,0,1]
	v_pk_fma_f32 v[12:13], v[52:53], v[46:47], v[16:17] op_sel_hi:[1,0,1]
	s_nop 0
	v_mov_b32_e32 v57, v13
	ds_write_b64 v54, v[56:57] offset:10240
	s_cbranch_scc1 .Lkh_b_5
	v_add_u32_e32 v12, 0xd00, v20
	v_ashrrev_i32_e32 v13, 31, v12
	v_lshl_add_u64 v[12:13], v[12:13], 3, s[0:1]
	global_load_dwordx2 v[46:47], v[12:13], off
.Lkh_b_5:
	v_add_u32_e32 v54, 0x700, v20
	v_and_b32_e32 v54, -8, v54
	v_add_u32_e32 v54, v9, v54
	ds_read_b64 v[52:53], v54 offset:14336
	s_waitcnt lgkmcnt(2)
	v_pk_mul_f32 v[16:17], v[14:15], v[48:49] op_sel:[1,1] op_sel_hi:[0,1]
	v_pk_fma_f32 v[18:19], v[14:15], v[48:49], v[16:17] neg_lo:[0,0,1] neg_hi:[0,0,1]
	v_pk_fma_f32 v[12:13], v[14:15], v[48:49], v[16:17] op_sel_hi:[1,0,1]
	s_nop 0
	v_mov_b32_e32 v19, v13
	ds_write_b64 v21, v[18:19] offset:12288
	s_cbranch_scc1 .Lkh_b_6
	v_add_u32_e32 v12, 0xe00, v20
	v_ashrrev_i32_e32 v13, 31, v12
	v_lshl_add_u64 v[12:13], v[12:13], 3, s[0:1]
	global_load_dwordx2 v[48:49], v[12:13], off
.Lkh_b_6:
	s_waitcnt lgkmcnt(1)
	v_pk_mul_f32 v[16:17], v[52:53], v[50:51] op_sel:[1,1] op_sel_hi:[0,1]
	v_pk_fma_f32 v[56:57], v[52:53], v[50:51], v[16:17] neg_lo:[0,0,1] neg_hi:[0,0,1]
	v_pk_fma_f32 v[12:13], v[52:53], v[50:51], v[16:17] op_sel_hi:[1,0,1]
	s_nop 0
	v_mov_b32_e32 v57, v13
	ds_write_b64 v54, v[56:57] offset:14336
	s_cbranch_scc1 .Lkh_b_7
	v_add_u32_e32 v12, 0xf00, v20
	v_ashrrev_i32_e32 v13, 31, v12
	v_lshl_add_u64 v[12:13], v[12:13], 3, s[0:1]
	global_load_dwordx2 v[50:51], v[12:13], off
.Lkh_b_7:
	v_add_u32_e32 v9, 0x4000, v9
	s_cbranch_scc0 .LBB0_476
	s_waitcnt lgkmcnt(0)
	s_barrier
	s_and_saveexec_b64 s[34:35], s[2:3]
	s_cbranch_execz .LBB0_487
	v_add_u32_e32 v9, 0xff, v65
	s_movk_i32 s0, 0x2100
	s_movk_i32 s4, 0x20ff
	v_cmp_gt_u32_e64 s[0:1], s0, v9
	v_cmp_lt_u32_e64 s[4:5], s4, v9
	v_mov_b32_e32 v10, v8
	s_and_saveexec_b64 s[20:21], s[4:5]
	s_cbranch_execz .LBB0_484
	v_lshrrev_b32_e32 v9, 8, v9
	s_movk_i32 s4, 0x48
	v_mul_lo_u32 v10, v8, s4
	v_mul_hi_u32_u24_e32 v11, 0x4800, v9
	s_movk_i32 s6, 0x4800
	v_cmp_ne_u32_e64 s[4:5], 0, v11
	v_mad_u32_u24 v11, v9, s6, v10
	v_cmp_lt_u32_e64 s[6:7], v11, v10
	v_add_u32_e32 v12, 8, v10
	v_add_u32_e32 v13, 8, v11
	s_or_b64 s[22:23], s[6:7], s[4:5]
	v_cmp_lt_u32_e64 s[6:7], v13, v12
	v_add_u32_e32 v12, 12, v10
	v_add_u32_e32 v13, 12, v11
	s_or_b64 s[24:25], s[6:7], s[4:5]
	v_cmp_lt_u32_e64 s[6:7], v13, v12
	v_add_u32_e32 v12, 16, v10
	v_add_u32_e32 v13, 16, v11
	s_or_b64 s[28:29], s[6:7], s[4:5]
	v_cmp_lt_u32_e64 s[6:7], v13, v12
	v_add_u32_e32 v12, 20, v10
	v_add_u32_e32 v13, 20, v11
	s_or_b64 s[30:31], s[6:7], s[4:5]
	v_cmp_lt_u32_e64 s[6:7], v13, v12
	v_add_u32_e32 v12, 24, v10
	v_add_u32_e32 v13, 24, v11
	s_or_b64 s[36:37], s[6:7], s[4:5]
	v_cmp_lt_u32_e64 s[6:7], v13, v12
	v_add_u32_e32 v12, 28, v10
	v_add_u32_e32 v13, 28, v11
	s_or_b64 s[38:39], s[6:7], s[4:5]
	v_cmp_lt_u32_e64 s[6:7], v13, v12
	v_add_u32_e32 v12, 32, v10
	v_add_u32_e32 v13, 32, v11
	s_or_b64 s[40:41], s[6:7], s[4:5]
	v_cmp_lt_u32_e64 s[6:7], v13, v12
	v_add_u32_e32 v12, 36, v10
	v_add_u32_e32 v13, 36, v11
	s_or_b64 s[42:43], s[6:7], s[4:5]
	v_cmp_lt_u32_e64 s[6:7], v13, v12
	v_add_u32_e32 v12, 40, v10
	v_add_u32_e32 v13, 40, v11
	s_or_b64 s[44:45], s[6:7], s[4:5]
	v_cmp_lt_u32_e64 s[6:7], v13, v12
	v_add_u32_e32 v12, 44, v10
	v_add_u32_e32 v13, 44, v11
	s_or_b64 s[46:47], s[6:7], s[4:5]
	v_cmp_lt_u32_e64 s[6:7], v13, v12
	v_add_u32_e32 v12, 48, v10
	v_add_u32_e32 v13, 48, v11
	s_or_b64 s[48:49], s[6:7], s[4:5]
	v_cmp_lt_u32_e64 s[6:7], v13, v12
	v_add_u32_e32 v12, 52, v10
	v_add_u32_e32 v13, 52, v11
	s_or_b64 s[50:51], s[6:7], s[4:5]
	v_cmp_lt_u32_e64 s[6:7], v13, v12
	v_add_u32_e32 v12, 56, v10
	v_add_u32_e32 v13, 56, v11
	s_or_b64 s[60:61], s[6:7], s[4:5]
	v_cmp_lt_u32_e64 s[6:7], v13, v12
	v_add_u32_e32 v10, 60, v10
	v_add_u32_e32 v11, 60, v11
	s_or_b64 s[96:97], s[6:7], s[4:5]
	v_cmp_lt_u32_e64 s[6:7], v11, v10
	s_or_b64 s[4:5], s[6:7], s[4:5]
	s_or_b64 s[6:7], s[22:23], s[24:25]
	s_or_b64 s[6:7], s[6:7], s[28:29]
	s_or_b64 s[6:7], s[6:7], s[30:31]
	s_or_b64 s[6:7], s[6:7], s[36:37]
	s_or_b64 s[6:7], s[6:7], s[38:39]
	s_or_b64 s[6:7], s[6:7], s[40:41]
	s_or_b64 s[6:7], s[6:7], s[42:43]
	s_or_b64 s[6:7], s[6:7], s[44:45]
	s_or_b64 s[6:7], s[6:7], s[46:47]
	s_or_b64 s[6:7], s[6:7], s[48:49]
	s_or_b64 s[6:7], s[6:7], s[50:51]
	s_or_b64 s[6:7], s[6:7], s[60:61]
	s_or_b64 s[6:7], s[6:7], s[96:97]
	s_nor_b64 s[22:23], s[6:7], s[4:5]
	s_mov_b64 s[4:5], -1
	v_mov_b32_e32 v10, v8
	s_and_saveexec_b64 s[6:7], s[22:23]
	s_cbranch_execz .LBB0_483
	v_add_u32_e32 v44, 1, v9
	v_and_b32_e32 v45, 0x1fffffe, v44
	v_add_u32_e32 v9, 0x100, v8
	s_mov_b64 s[22:23], 0
	v_mov_b32_e32 v46, v45
	v_mov_b64_e32 v[10:11], v[8:9]
